# P6 K-loop: skip first two vmcnt(8) waits of a unit that follows an epilogue (its vmcnt(0) already retired the prefetched K-tiles; avoids waiting on epilogue store acks)
# speedup vs baseline: 1.0016x; 1.0016x over previous
; DI int tid_of(int wave0) { int t = wave0 * 64 + lane_id(); asm volatile("" : "+v"(t)); return t; }
;     __host__ __device__ bool next(int i, Unit& u) const { return at((long)i * G + c, u); }
;     __host__ __device__ bool next(int i, Unit& u) const { if (i != 0 || c >= cnt) return false; u.pm = pm0 + c / nN; u.pn = c % nN; u.k0 = 0; u.nt = ntk; return true; }
; #define PG8_WAIT_V(n) asm volatile("s_waitcnt vmcnt(" #n ")" ::: "memory")
; #define PG8_BAR __builtin_amdgcn_s_barrier()
;     const int tid = tid_of(wave0), wid = wave0, lane = tid & 63, wr = wid >> 2, wc = wid & 3, fr = lane & 15, fq = lane >> 4;
;     const int K = g.K;
;     unsigned voffA[2], voffB[2];
; #pragma unroll
;     for (int i = 0; i < 2; ++i) { int R, C; stage_rc(tid * 16 + i * 8192, R, C); const int Rb = (R >> 5) * 64 + (Epi::PERM ? perm32(R & 31) : (R & 31));
;         voffA[i] = (unsigned)(R * K + C) * 2u; voffB[i] = (unsigned)(Rb * K + C) * 2u; }
;     const size_t kstep = (size_t)(BK * 2);
;     const size_t hstep = (size_t)HALF * K * 2;
;     const size_t tstep = 2 * hstep;
;     const size_t hstepB = (size_t)32 * K * 2;
;     const unsigned ldsw = (unsigned)wid * 1024u;
;     const int aoff = lds_byte(wr * 64 + fr, fq * 8), boff = lds_byte(wc * 32 + fr, fq * 8);
;     ...
;     Unit cur, nxt; int ui = 0;
;     if (!S.next(0, cur)) return;
;     f32x4 acc[2][2][4][2];
; #pragma unroll
;     for (int a = 0; a < 2; ++a)
; #pragma unroll
;         for (int b = 0; b < 2; ++b)
; #pragma unroll
;             for (int m = 0; m < 4; ++m)
; #pragma unroll
;                 for (int n = 0; n < 2; ++n) acc[a][b][m][n] = (f32x4){0.f, 0.f, 0.f, 0.f};
;     bf16x8 At[4][2], B0[2][2], B1[2][2];
;     const char* cA = (const char*)g.A + (size_t)cur.pm * tstep + (size_t)cur.k0 * (BK * 2); const char* cB = (const char*)g.Bt + (size_t)cur.pn * tstep + (size_t)cur.k0 * (BK * 2);
;     S.a_ready(cur);
;     if constexpr (SP2) {
;         PG8_STAGE(PG8_SB(0, 0), cB, voffB); PG8_STAGE(PG8_SB(0, 1), cB + hstepB, voffB); PG8_STAGEA(PG8_SA(0, 0), cA, voffA); PG8_STAGEA(PG8_SA(0, 1), cA + hstep, voffA);
;         if (wr == 1) PG8_BAR;
;         PG8_WAIT_V(2); PG8_BAR;
;         PG8_STAGE(PG8_SB(1, 0), cB + kstep, voffB); PG8_STAGEA(PG8_SA(1, 0), cA + kstep, voffA); PG8_STAGE(PG8_SB(1, 1), cB + hstepB + kstep, voffB);
;         PG8_WAIT_V(6); PG8_BAR;
.LBB0_971:
	s_mov_b64 s[16:17], 0x80
	s_add_i32 m0, s37, 0x18000
	v_lshl_add_u64 v[4:5], v[4:5], 0, s[16:17]
	s_waitcnt vmcnt(2)
	s_barrier
	global_load_lds_dwordx4 v[4:5], off
	v_lshl_add_u64 v[2:3], v[2:3], 0, s[16:17]
	s_add_i32 m0, s37, 0x1a000
	s_add_i32 s51, s37, 0x8000
	s_add_i32 s52, s37, 0xa000
	global_load_lds_dwordx4 v[2:3], off
	v_lshl_add_u64 v[0:1], v[0:1], 0, s[16:17]
	s_mov_b32 m0, s51
	s_add_u32 s0, s40, 0x10080
	global_load_lds_dwordx4 v[0:1], off
	v_lshl_add_u64 v[0:1], v[6:7], 0, s[16:17]
	s_mov_b32 m0, s52
	s_addc_u32 s1, s41, 0
	global_load_lds_dwordx4 v[0:1], off
	s_add_i32 m0, s37, 0x1c000
	v_lshl_add_u64 v[0:1], s[0:1], 0, v[132:133]
	global_load_lds_dwordx4 v[0:1], off
	v_lshl_add_u64 v[0:1], s[0:1], 0, v[128:129]
	s_add_i32 m0, s37, 0x1e000
	s_movk_i32 s0, 0x3c0
	global_load_lds_dwordx4 v[0:1], off
	v_and_b32_e32 v1, 15, v10
	v_lshrrev_b32_e32 v0, 1, v10
	v_or_b32_e32 v168, s72, v1
	v_and_b32_e32 v0, 24, v0
	v_lshlrev_b32_e32 v2, 6, v168
	v_lshlrev_b32_e32 v3, 1, v0
	v_lshlrev_b32_e32 v4, 2, v168
	v_and_or_b32 v2, v2, s0, v3
	v_and_b32_e32 v4, 32, v4
	v_readlane_b32 s0, v255, 18
	v_lshl_or_b32 v1, v1, 6, v3
	v_lshlrev_b32_e32 v3, 2, v10
	v_bitop3_b32 v2, v2, s0, v4 bitop3:0xde
	v_and_b32_e32 v3, 32, v3
	v_readlane_b32 s0, v255, 19
	s_waitcnt vmcnt(6)
	v_mov_b32_e32 v139, v137
	v_mov_b32_e32 v141, v137
	v_bitop3_b32 v169, v1, s0, v3 bitop3:0xde
	v_lshlrev_b32_e32 v1, 14, v13
	v_and_b32_e32 v1, 0xffff8000, v1
	v_lshl_add_u32 v1, v12, 11, v1
	v_and_b32_e32 v3, 1, v13
	v_lshl_or_b32 v1, v3, 6, v1
	v_lshl_add_u32 v138, v14, 1, v1
	v_lshlrev_b32_e32 v1, 14, v8
	v_readlane_b32 s0, v255, 10
	v_and_b32_e32 v1, 0xffff8000, v1
	s_cmpk_lt_u32 s0, 0x100
	v_lshl_add_u32 v1, v9, 11, v1
	v_and_b32_e32 v3, 1, v8
	s_cselect_b64 s[18:19], -1, 0
	s_lshl_b32 s0, s48, 6
	v_lshl_or_b32 v1, v3, 6, v1
	s_add_i32 s54, 0, 0x10000
	s_add_i32 s55, 0, 0x14000
	s_ashr_i32 s53, s96, 31
	v_lshl_add_u32 v140, v11, 1, v1
	v_mov_b64_e32 v[142:143], s[12:13]
	v_add_u32_e32 v170, s54, v169
	v_add_u32_e32 v171, s55, v169
	v_add_u32_e32 v172, 0, v2
	s_lshl_b32 s12, s0, 1
	v_lshlrev_b32_e32 v136, 1, v0
	s_mov_b32 s20, 0x3a800000
	s_mov_b32 s22, 0x358637bd
	s_mov_b32 s56, 0x800000
	s_mov_b32 s57, s13
	s_barrier
	s_mov_b32 s99, 0
	s_branch .LBB0_974

;     __host__ __device__ bool next(int i, Unit& u) const { return at((long)i * G + c, u); }
;     __host__ __device__ bool next(int i, Unit& u) const { if (i != 0 || c >= cnt) return false; u.pm = pm0 + c / nN; u.pn = c % nN; u.k0 = 0; u.nt = ntk; return true; }
; #define PG8_BAR __builtin_amdgcn_s_barrier()
;     ...
;     for (;;) {
;         const bool has_next = S.next(ui + 1, nxt);
;         const char* nA = has_next ? (const char*)g.A + (size_t)nxt.pm * tstep + (size_t)nxt.k0 * (BK * 2) : cA; const char* nB = has_next ? (const char*)g.Bt + (size_t)nxt.pn * tstep + (size_t)nxt.k0 * (BK * 2) : cB;
;         const int nt = cur.nt;
;     ...
;         cur = nxt; cA = nA; cB = nB; ++ui;
;         if constexpr (ALIGN_EPI) { if (wr == 1) PG8_BAR; }
;     }
.LBB0_973:
	s_mov_b32 s99, 1
	s_andn2_b64 vcc, exec, s[0:1]
	s_mov_b32 s34, s24
	s_mov_b32 s36, s26
	s_mov_b64 s[40:41], s[30:31]
	s_mov_b64 s[38:39], s[28:29]
	s_cbranch_vccz .LBB0_983

; #define PG8_STAGE(bufoff, gbase, voff) do { _Pragma("unroll") for (int _i = 0; _i < 2; ++_i) \
;         __builtin_amdgcn_global_load_lds((const unsigned*)((const char*)(gbase) + (voff)[_i]), (PG8_LAS unsigned*)(lds + (bufoff) + ldsw + _i * 8192), 16, 0, 0); } while (0)
; #define PG8_STAGEA(bufoff, gbase, voff) do { _Pragma("unroll") for (int _i = 0; _i < 2; ++_i) \
;         __builtin_amdgcn_global_load_lds((const unsigned*)((const char*)(gbase) + (voff)[_i]), (PG8_LAS unsigned*)(lds + (bufoff) + ldsw + _i * 8192), 16, 0, AUXA); } while (0)
; #define PG8_LDA(dst, b, h) do { _Pragma("unroll") for (int m = 0; m < 4; ++m) _Pragma("unroll") for (int k = 0; k < 2; ++k) dst[m][k] = *(const PG8_LAS bf16x8*)(lds + PG8_SA(b, h) + aoff + m * 2048 + k * 1024); } while (0)
; #define PG8_LDB(dst, b, h) do { _Pragma("unroll") for (int n = 0; n < 2; ++n) _Pragma("unroll") for (int k = 0; k < 2; ++k) dst[n][k] = *(const PG8_LAS bf16x8*)(lds + PG8_SB(b, h) + boff + n * 2048 + k * 1024); } while (0)
; #define PG8_MMA(ai, bj, At, Bt) do { __builtin_amdgcn_s_setprio(1); _Pragma("unroll") for (int m = 0; m < 4; ++m) _Pragma("unroll") for (int n = 0; n < 2; ++n) _Pragma("unroll") for (int k = 0; k < 2; ++k) \
;         acc[ai][bj][m][n] = __builtin_amdgcn_mfma_f32_16x16x32_bf16(Bt[n][k], At[m][k], acc[ai][bj][m][n], 0, 0, 0); __builtin_amdgcn_s_setprio(0); } while (0)
; #define PG8_WAIT_V(n) asm volatile("s_waitcnt vmcnt(" #n ")" ::: "memory")
; #define PG8_WAIT_L(n) asm volatile("s_waitcnt lgkmcnt(" #n ")" ::: "memory")
; #define PG8_BAR __builtin_amdgcn_s_barrier()
; #define PG8_SCHED __builtin_amdgcn_sched_barrier(0)
;     ...
;             PG8_LDB(B0, 0, 0); PG8_LDB(B1, 0, 1); PG8_SCHED; PG8_LDA(At, 0, 0); PG8_STAGEA(PG8_SA(1, 1), a1 + hstep, voffA);
;             PG8_WAIT_V(8); PG8_WAIT_L(0); PG8_BAR; PG8_MMA(0, 0, At, B0); PG8_MMA(0, 1, At, B1); PG8_BAR; PG8_SCHED;
;             PG8_LDA(At, 0, 1); PG8_STAGE(PG8_SB(0, 0), b2, voffB); PG8_STAGE(PG8_SB(0, 1), b2 + hstepB, voffB); PG8_STAGEA(PG8_SA(0, 0), a2, voffA);
.Lsprio_5:
.LBB0_977:
	ds_read_b128 v[144:147], v170
	ds_read_b128 v[148:151], v170 offset:1024
	ds_read_b128 v[152:155], v170 offset:2048
	ds_read_b128 v[156:159], v170 offset:3072
	ds_read_b128 v[160:163], v171
	ds_read_b128 v[164:167], v171 offset:1024
	ds_read_b128 v[176:179], v171 offset:2048
	ds_read_b128 v[180:183], v171 offset:3072
	s_add_u32 s40, s38, 0xfffc0080
	s_addc_u32 s41, s39, -1
	s_cmp_eq_u32 s71, 12
	s_cselect_b32 s43, s27, s41
	s_cselect_b32 s42, s35, s40
	s_cselect_b32 s41, s25, s70
	s_cselect_b32 s40, s58, s59
	v_lshl_add_u64 v[206:207], s[38:39], 0, v[138:139]
	s_add_i32 m0, s37, 0xc000
	ds_read_b128 v[184:187], v172
	ds_read_b128 v[188:191], v172 offset:1024
	ds_read_b128 v[192:195], v172 offset:2048
	ds_read_b128 v[196:199], v172 offset:3072
	ds_read_b128 v[202:205], v172 offset:4096
	ds_read_b128 v[210:213], v172 offset:5120
	ds_read_b128 v[214:217], v172 offset:6144
	ds_read_b128 v[218:221], v172 offset:7168
	global_load_lds_dwordx4 v[206:207], off
	v_lshl_add_u64 v[206:207], s[38:39], 0, v[140:141]
	s_add_i32 m0, s37, 0xe000
	s_nop 0
	global_load_lds_dwordx4 v[206:207], off
	s_cmp_lg_u32 s99, 0
	s_cbranch_scc1 .Lfiw_p6_1
	s_waitcnt vmcnt(8)
.Lfiw_p6_1:
	s_waitcnt lgkmcnt(0)
	s_barrier
	s_waitcnt lgkmcnt(0)
	v_mfma_f32_16x16x32_bf16 v[124:127], v[144:147], v[184:187], v[124:127]
	v_mfma_f32_16x16x32_bf16 v[120:123], v[152:155], v[184:187], v[120:123]
	v_mfma_f32_16x16x32_bf16 v[108:111], v[144:147], v[192:195], v[108:111]
	v_mfma_f32_16x16x32_bf16 v[104:107], v[152:155], v[192:195], v[104:107]
	v_mfma_f32_16x16x32_bf16 v[92:95], v[144:147], v[202:205], v[92:95]
	v_mfma_f32_16x16x32_bf16 v[88:91], v[152:155], v[202:205], v[88:91]
	v_mfma_f32_16x16x32_bf16 v[76:79], v[144:147], v[214:217], v[76:79]
	v_mfma_f32_16x16x32_bf16 v[72:75], v[152:155], v[214:217], v[72:75]
	v_mfma_f32_16x16x32_bf16 v[124:127], v[148:151], v[188:191], v[124:127]
	v_mfma_f32_16x16x32_bf16 v[120:123], v[156:159], v[188:191], v[120:123]
	v_mfma_f32_16x16x32_bf16 v[108:111], v[148:151], v[196:199], v[108:111]
	v_mfma_f32_16x16x32_bf16 v[104:107], v[156:159], v[196:199], v[104:107]
	v_mfma_f32_16x16x32_bf16 v[92:95], v[148:151], v[210:213], v[92:95]
	v_mfma_f32_16x16x32_bf16 v[88:91], v[156:159], v[210:213], v[88:91]
	v_mfma_f32_16x16x32_bf16 v[76:79], v[148:151], v[218:221], v[76:79]
	v_mfma_f32_16x16x32_bf16 v[72:75], v[156:159], v[218:221], v[72:75]
	v_mfma_f32_16x16x32_bf16 v[116:119], v[160:163], v[184:187], v[116:119]
	v_mfma_f32_16x16x32_bf16 v[112:115], v[176:179], v[184:187], v[112:115]
	v_mfma_f32_16x16x32_bf16 v[100:103], v[160:163], v[192:195], v[100:103]
	v_mfma_f32_16x16x32_bf16 v[96:99], v[176:179], v[192:195], v[96:99]
	v_mfma_f32_16x16x32_bf16 v[84:87], v[160:163], v[202:205], v[84:87]
	v_mfma_f32_16x16x32_bf16 v[80:83], v[176:179], v[202:205], v[80:83]
	v_mfma_f32_16x16x32_bf16 v[68:71], v[160:163], v[214:217], v[68:71]
	v_mfma_f32_16x16x32_bf16 v[64:67], v[176:179], v[214:217], v[64:67]
	v_mfma_f32_16x16x32_bf16 v[116:119], v[164:167], v[188:191], v[116:119]
	v_mfma_f32_16x16x32_bf16 v[112:115], v[180:183], v[188:191], v[112:115]
	v_mfma_f32_16x16x32_bf16 v[100:103], v[164:167], v[196:199], v[100:103]
	v_mfma_f32_16x16x32_bf16 v[96:99], v[180:183], v[196:199], v[96:99]
	v_mfma_f32_16x16x32_bf16 v[84:87], v[164:167], v[210:213], v[84:87]
	v_mfma_f32_16x16x32_bf16 v[80:83], v[180:183], v[210:213], v[80:83]
	v_mfma_f32_16x16x32_bf16 v[68:71], v[164:167], v[218:221], v[68:71]
	v_mfma_f32_16x16x32_bf16 v[64:67], v[180:183], v[218:221], v[64:67]
	s_barrier
	s_add_i32 s73, s54, s67
	v_lshl_add_u64 v[206:207], s[40:41], 0, v[132:133]
	s_mov_b32 m0, s73
	ds_read_b128 v[184:187], v172 offset:16384
	ds_read_b128 v[188:191], v172 offset:17408
	ds_read_b128 v[192:195], v172 offset:18432
	ds_read_b128 v[196:199], v172 offset:19456
	ds_read_b128 v[202:205], v172 offset:20480
	ds_read_b128 v[210:213], v172 offset:21504
	ds_read_b128 v[214:217], v172 offset:22528
	ds_read_b128 v[218:221], v172 offset:23552
	global_load_lds_dwordx4 v[206:207], off
	s_add_i32 m0, s73, 0x2000
	s_add_u32 s74, s40, 0x10000
	v_lshl_add_u64 v[222:223], s[40:41], 0, v[128:129]
	s_addc_u32 s75, s41, 0
	s_add_i32 s73, s55, s67
	global_load_lds_dwordx4 v[222:223], off
	v_lshl_add_u64 v[224:225], s[74:75], 0, v[132:133]
	s_mov_b32 m0, s73
	v_lshl_add_u64 v[226:227], s[42:43], 0, v[130:131]
	global_load_lds_dwordx4 v[224:225], off
	v_lshl_add_u64 v[224:225], s[74:75], 0, v[128:129]
	s_add_i32 m0, s73, 0x2000
	s_nop 0
	global_load_lds_dwordx4 v[224:225], off
	v_lshl_add_u64 v[224:225], s[42:43], 0, v[134:135]
	s_mov_b32 m0, s37
	s_nop 0
	global_load_lds_dwordx4 v[224:225], off
	s_mov_b32 m0, s46
	s_nop 0
	global_load_lds_dwordx4 v[226:227], off
	s_cmp_lg_u32 s99, 0
	s_cbranch_scc1 .Lfiw_p6_0
	s_waitcnt vmcnt(8)
; #define PG8_STAGE(bufoff, gbase, voff) do { _Pragma("unroll") for (int _i = 0; _i < 2; ++_i) \
;         __builtin_amdgcn_global_load_lds((const unsigned*)((const char*)(gbase) + (voff)[_i]), (PG8_LAS unsigned*)(lds + (bufoff) + ldsw + _i * 8192), 16, 0, 0); } while (0)
; #define PG8_STAGEA(bufoff, gbase, voff) do { _Pragma("unroll") for (int _i = 0; _i < 2; ++_i) \
;         __builtin_amdgcn_global_load_lds((const unsigned*)((const char*)(gbase) + (voff)[_i]), (PG8_LAS unsigned*)(lds + (bufoff) + ldsw + _i * 8192), 16, 0, AUXA); } while (0)
; #define PG8_LDA(dst, b, h) do { _Pragma("unroll") for (int m = 0; m < 4; ++m) _Pragma("unroll") for (int k = 0; k < 2; ++k) dst[m][k] = *(const PG8_LAS bf16x8*)(lds + PG8_SA(b, h) + aoff + m * 2048 + k * 1024); } while (0)
; #define PG8_LDB(dst, b, h) do { _Pragma("unroll") for (int n = 0; n < 2; ++n) _Pragma("unroll") for (int k = 0; k < 2; ++k) dst[n][k] = *(const PG8_LAS bf16x8*)(lds + PG8_SB(b, h) + boff + n * 2048 + k * 1024); } while (0)
; #define PG8_MMA(ai, bj, At, Bt) do { __builtin_amdgcn_s_setprio(1); _Pragma("unroll") for (int m = 0; m < 4; ++m) _Pragma("unroll") for (int n = 0; n < 2; ++n) _Pragma("unroll") for (int k = 0; k < 2; ++k) \
;         acc[ai][bj][m][n] = __builtin_amdgcn_mfma_f32_16x16x32_bf16(Bt[n][k], At[m][k], acc[ai][bj][m][n], 0, 0, 0); __builtin_amdgcn_s_setprio(0); } while (0)
; #define PG8_WAIT_V(n) asm volatile("s_waitcnt vmcnt(" #n ")" ::: "memory")
; #define PG8_WAIT_L(n) asm volatile("s_waitcnt lgkmcnt(" #n ")" ::: "memory")
; #define PG8_BAR __builtin_amdgcn_s_barrier()
; #define PG8_SCHED __builtin_amdgcn_sched_barrier(0)
;     ...
;             PG8_LDA(At, 0, 1); PG8_STAGE(PG8_SB(0, 0), b2, voffB); PG8_STAGE(PG8_SB(0, 1), b2 + hstepB, voffB); PG8_STAGEA(PG8_SA(0, 0), a2, voffA);
;             PG8_WAIT_V(8); PG8_WAIT_L(0); PG8_BAR; PG8_MMA(1, 0, At, B0); PG8_MMA(1, 1, At, B1); PG8_BAR; PG8_SCHED;
;             PG8_LDB(B0, 1, 0); PG8_LDB(B1, 1, 1); PG8_SCHED; PG8_LDA(At, 1, 0); PG8_STAGEA(PG8_SA(0, 1), a2 + hstep, voffA);
;             PG8_WAIT_V(8); PG8_WAIT_L(0); PG8_BAR; PG8_MMA(0, 0, At, B0); PG8_MMA(0, 1, At, B1); PG8_BAR; PG8_SCHED;
.Lfiw_p6_0:
	s_waitcnt lgkmcnt(0)
	s_barrier
	s_waitcnt lgkmcnt(0)
	v_mfma_f32_16x16x32_bf16 v[60:63], v[144:147], v[184:187], v[60:63]
	v_mfma_f32_16x16x32_bf16 v[56:59], v[152:155], v[184:187], v[56:59]
	v_mfma_f32_16x16x32_bf16 v[44:47], v[144:147], v[192:195], v[44:47]
	v_mfma_f32_16x16x32_bf16 v[40:43], v[152:155], v[192:195], v[40:43]
	v_mfma_f32_16x16x32_bf16 v[28:31], v[144:147], v[202:205], v[28:31]
	v_mfma_f32_16x16x32_bf16 v[24:27], v[152:155], v[202:205], v[24:27]
	v_mfma_f32_16x16x32_bf16 v[12:15], v[144:147], v[214:217], v[12:15]
	v_mfma_f32_16x16x32_bf16 v[8:11], v[152:155], v[214:217], v[8:11]
	v_mfma_f32_16x16x32_bf16 v[60:63], v[148:151], v[188:191], v[60:63]
	v_mfma_f32_16x16x32_bf16 v[56:59], v[156:159], v[188:191], v[56:59]
	v_mfma_f32_16x16x32_bf16 v[44:47], v[148:151], v[196:199], v[44:47]
	v_mfma_f32_16x16x32_bf16 v[40:43], v[156:159], v[196:199], v[40:43]
	v_mfma_f32_16x16x32_bf16 v[28:31], v[148:151], v[210:213], v[28:31]
	v_mfma_f32_16x16x32_bf16 v[24:27], v[156:159], v[210:213], v[24:27]
	v_mfma_f32_16x16x32_bf16 v[12:15], v[148:151], v[218:221], v[12:15]
	v_mfma_f32_16x16x32_bf16 v[8:11], v[156:159], v[218:221], v[8:11]
	v_mfma_f32_16x16x32_bf16 v[52:55], v[160:163], v[184:187], v[52:55]
	v_mfma_f32_16x16x32_bf16 v[48:51], v[176:179], v[184:187], v[48:51]
	v_mfma_f32_16x16x32_bf16 v[36:39], v[160:163], v[192:195], v[36:39]
	v_mfma_f32_16x16x32_bf16 v[32:35], v[176:179], v[192:195], v[32:35]
	v_mfma_f32_16x16x32_bf16 v[20:23], v[160:163], v[202:205], v[20:23]
	v_mfma_f32_16x16x32_bf16 v[16:19], v[176:179], v[202:205], v[16:19]
	v_mfma_f32_16x16x32_bf16 v[4:7], v[160:163], v[214:217], v[4:7]
	v_mfma_f32_16x16x32_bf16 v[0:3], v[176:179], v[214:217], v[0:3]
	v_mfma_f32_16x16x32_bf16 v[52:55], v[164:167], v[188:191], v[52:55]
	v_mfma_f32_16x16x32_bf16 v[48:51], v[180:183], v[188:191], v[48:51]
	v_mfma_f32_16x16x32_bf16 v[36:39], v[164:167], v[196:199], v[36:39]
	v_mfma_f32_16x16x32_bf16 v[32:35], v[180:183], v[196:199], v[32:35]
	v_mfma_f32_16x16x32_bf16 v[20:23], v[164:167], v[210:213], v[20:23]
	v_mfma_f32_16x16x32_bf16 v[16:19], v[180:183], v[210:213], v[16:19]
	v_mfma_f32_16x16x32_bf16 v[4:7], v[164:167], v[218:221], v[4:7]
	v_mfma_f32_16x16x32_bf16 v[0:3], v[180:183], v[218:221], v[0:3]
	s_barrier
	s_add_i32 s73, 0, 0x18000
	s_add_i32 s74, 0, 0x1c000
	v_add_u32_e32 v156, s73, v169
	v_add_u32_e32 v173, s74, v169
	ds_read_b128 v[144:147], v156
	ds_read_b128 v[148:151], v156 offset:1024
	ds_read_b128 v[152:155], v156 offset:2048
	ds_read_b128 v[156:159], v156 offset:3072
	ds_read_b128 v[160:163], v173
	ds_read_b128 v[164:167], v173 offset:1024
	ds_read_b128 v[176:179], v173 offset:2048
	ds_read_b128 v[180:183], v173 offset:3072
	s_add_u32 s42, s42, 0x40000
	s_addc_u32 s43, s43, 0
	s_mov_b32 m0, s47
	v_lshl_add_u64 v[228:229], s[42:43], 0, v[134:135]
	ds_read_b128 v[184:187], v172 offset:32768
	ds_read_b128 v[188:191], v172 offset:33792
	ds_read_b128 v[192:195], v172 offset:34816
	ds_read_b128 v[196:199], v172 offset:35840
	ds_read_b128 v[202:205], v172 offset:36864
	ds_read_b128 v[210:213], v172 offset:37888
	ds_read_b128 v[214:217], v172 offset:38912
	ds_read_b128 v[218:221], v172 offset:39936
	global_load_lds_dwordx4 v[228:229], off
	v_lshl_add_u64 v[228:229], s[42:43], 0, v[130:131]
	s_mov_b32 m0, s50
	s_nop 0
	global_load_lds_dwordx4 v[228:229], off
	s_mov_b32 s99, 0
	s_waitcnt vmcnt(8)
	s_waitcnt lgkmcnt(0)
	s_barrier
	s_waitcnt lgkmcnt(0)
	v_mfma_f32_16x16x32_bf16 v[124:127], v[144:147], v[184:187], v[124:127]
	v_mfma_f32_16x16x32_bf16 v[120:123], v[152:155], v[184:187], v[120:123]
	v_mfma_f32_16x16x32_bf16 v[108:111], v[144:147], v[192:195], v[108:111]
	v_mfma_f32_16x16x32_bf16 v[104:107], v[152:155], v[192:195], v[104:107]
	v_mfma_f32_16x16x32_bf16 v[92:95], v[144:147], v[202:205], v[92:95]
	v_mfma_f32_16x16x32_bf16 v[88:91], v[152:155], v[202:205], v[88:91]
	v_mfma_f32_16x16x32_bf16 v[76:79], v[144:147], v[214:217], v[76:79]
	v_mfma_f32_16x16x32_bf16 v[72:75], v[152:155], v[214:217], v[72:75]
	v_mfma_f32_16x16x32_bf16 v[124:127], v[148:151], v[188:191], v[124:127]
	v_mfma_f32_16x16x32_bf16 v[120:123], v[156:159], v[188:191], v[120:123]
	v_mfma_f32_16x16x32_bf16 v[108:111], v[148:151], v[196:199], v[108:111]
	v_mfma_f32_16x16x32_bf16 v[104:107], v[156:159], v[196:199], v[104:107]
	v_mfma_f32_16x16x32_bf16 v[92:95], v[148:151], v[210:213], v[92:95]
	v_mfma_f32_16x16x32_bf16 v[88:91], v[156:159], v[210:213], v[88:91]
	v_mfma_f32_16x16x32_bf16 v[76:79], v[148:151], v[218:221], v[76:79]
	v_mfma_f32_16x16x32_bf16 v[72:75], v[156:159], v[218:221], v[72:75]
	v_mfma_f32_16x16x32_bf16 v[116:119], v[160:163], v[184:187], v[116:119]
	v_mfma_f32_16x16x32_bf16 v[112:115], v[176:179], v[184:187], v[112:115]
	v_mfma_f32_16x16x32_bf16 v[100:103], v[160:163], v[192:195], v[100:103]
	v_mfma_f32_16x16x32_bf16 v[96:99], v[176:179], v[192:195], v[96:99]
	v_mfma_f32_16x16x32_bf16 v[84:87], v[160:163], v[202:205], v[84:87]
	v_mfma_f32_16x16x32_bf16 v[80:83], v[176:179], v[202:205], v[80:83]
	v_mfma_f32_16x16x32_bf16 v[68:71], v[160:163], v[214:217], v[68:71]
	v_mfma_f32_16x16x32_bf16 v[64:67], v[176:179], v[214:217], v[64:67]
	v_mfma_f32_16x16x32_bf16 v[116:119], v[164:167], v[188:191], v[116:119]
	v_mfma_f32_16x16x32_bf16 v[112:115], v[180:183], v[188:191], v[112:115]
	v_mfma_f32_16x16x32_bf16 v[100:103], v[164:167], v[196:199], v[100:103]
	v_mfma_f32_16x16x32_bf16 v[96:99], v[180:183], v[196:199], v[96:99]
	v_mfma_f32_16x16x32_bf16 v[84:87], v[164:167], v[210:213], v[84:87]
	v_mfma_f32_16x16x32_bf16 v[80:83], v[180:183], v[210:213], v[80:83]
	v_mfma_f32_16x16x32_bf16 v[68:71], v[164:167], v[218:221], v[68:71]
	v_mfma_f32_16x16x32_bf16 v[64:67], v[180:183], v[218:221], v[64:67]
	s_barrier
; #define PG8_STAGE(bufoff, gbase, voff) do { _Pragma("unroll") for (int _i = 0; _i < 2; ++_i) \
;         __builtin_amdgcn_global_load_lds((const unsigned*)((const char*)(gbase) + (voff)[_i]), (PG8_LAS unsigned*)(lds + (bufoff) + ldsw + _i * 8192), 16, 0, 0); } while (0)
; #define PG8_STAGEA(bufoff, gbase, voff) do { _Pragma("unroll") for (int _i = 0; _i < 2; ++_i) \
;         __builtin_amdgcn_global_load_lds((const unsigned*)((const char*)(gbase) + (voff)[_i]), (PG8_LAS unsigned*)(lds + (bufoff) + ldsw + _i * 8192), 16, 0, AUXA); } while (0)
; #define PG8_BAR __builtin_amdgcn_s_barrier()
;     ...
;             PG8_LDA(At, 1, 1); PG8_STAGE(PG8_SB(1, 0), b3, voffB); PG8_STAGE(PG8_SB(1, 1), b3 + hstepB, voffB); PG8_STAGEA(PG8_SA(1, 0), a3, voffA);
;             PG8_WAIT_V(8); PG8_WAIT_L(0); PG8_BAR; PG8_MMA(1, 0, At, B0); PG8_MMA(1, 1, At, B1); PG8_BAR; PG8_SCHED;
;             } else {
;             PG8_LDB(B0, 0, 0); PG8_SCHED; PG8_LDA(At, 0, 0); PG8_STAGEA(PG8_SA(1, 1), a1 + hstep, voffA);
;             PG8_WAIT_L(8); PG8_BAR; PG8_WAIT_L(0); PG8_MMA(0, 0, At, B0); PG8_BAR; PG8_SCHED;
;             PG8_LDB(B1, 0, 1); PG8_STAGE(PG8_SB(0, 0), b2, voffB);
;             PG8_BAR; PG8_WAIT_L(0); PG8_MMA(0, 1, At, B1); PG8_BAR;
;             PG8_LDA(At, 0, 1); PG8_STAGEA(PG8_SA(0, 0), a2, voffA);
;             PG8_BAR; PG8_WAIT_L(0); PG8_MMA(1, 0, At, B0); PG8_BAR; PG8_SCHED;
;             PG8_STAGE(PG8_SB(0, 1), b2 + hstepB, voffB);
;             PG8_WAIT_V(6); PG8_BAR; PG8_MMA(1, 1, At, B1); PG8_BAR;
;             PG8_LDB(B0, 1, 0); PG8_SCHED; PG8_LDA(At, 1, 0); PG8_STAGEA(PG8_SA(0, 1), a2 + hstep, voffA);
;             PG8_WAIT_L(8); PG8_BAR; PG8_WAIT_L(0); PG8_MMA(0, 0, At, B0); PG8_BAR; PG8_SCHED;
;             PG8_LDB(B1, 1, 1); PG8_STAGE(PG8_SB(1, 0), b3, voffB);
;             PG8_BAR; PG8_WAIT_L(0); PG8_MMA(0, 1, At, B1); PG8_BAR;
;             PG8_LDA(At, 1, 1); PG8_STAGEA(PG8_SA(1, 0), a3, voffA);
;             PG8_BAR; PG8_WAIT_L(0); PG8_MMA(1, 0, At, B0); PG8_BAR; PG8_SCHED;
;             PG8_STAGE(PG8_SB(1, 1), b3 + hstepB, voffB);
;             PG8_WAIT_V(6); PG8_BAR; PG8_MMA(1, 1, At, B1); PG8_BAR;
;             }
;         }
;         if constexpr (ALIGN_EPI) { if (wr == 0) PG8_BAR; }
;         if constexpr (!Epi::AFTER_DRAIN) { if (!(Epi::LAST_FUSED && !has_next)) { E(acc, cur, wr, wc, fr, fq); S.done(cur); } }
;         if (!has_next) break;
	s_add_i32 s42, s73, s67
	v_lshl_add_u64 v[206:207], v[206:207], 0, s[16:17]
	s_mov_b32 m0, s42
	ds_read_b128 v[184:187], v172 offset:49152
	ds_read_b128 v[188:191], v172 offset:50176
	ds_read_b128 v[192:195], v172 offset:51200
	ds_read_b128 v[196:199], v172 offset:52224
	ds_read_b128 v[202:205], v172 offset:53248
	ds_read_b128 v[210:213], v172 offset:54272
	ds_read_b128 v[214:217], v172 offset:55296
	ds_read_b128 v[218:221], v172 offset:56320
	global_load_lds_dwordx4 v[206:207], off
	s_add_i32 m0, s42, 0x2000
	s_add_u32 s40, s40, 0x10080
	v_lshl_add_u64 v[206:207], v[222:223], 0, s[16:17]
	s_addc_u32 s41, s41, 0
	s_add_i32 s42, s74, s67
	global_load_lds_dwordx4 v[206:207], off
	v_lshl_add_u64 v[206:207], s[40:41], 0, v[132:133]
	s_mov_b32 m0, s42
	s_nop 0
	global_load_lds_dwordx4 v[206:207], off
	v_lshl_add_u64 v[206:207], s[40:41], 0, v[128:129]
	s_add_i32 m0, s42, 0x2000
	s_nop 0
	global_load_lds_dwordx4 v[206:207], off
	v_lshl_add_u64 v[206:207], v[224:225], 0, s[16:17]
	s_mov_b32 m0, s51
	s_nop 0
	global_load_lds_dwordx4 v[206:207], off
	v_lshl_add_u64 v[206:207], v[226:227], 0, s[16:17]
	s_mov_b32 m0, s52
	s_nop 0
	global_load_lds_dwordx4 v[206:207], off
	s_waitcnt vmcnt(8)
	s_waitcnt lgkmcnt(0)
	s_barrier
	s_waitcnt lgkmcnt(0)
	v_mfma_f32_16x16x32_bf16 v[60:63], v[144:147], v[184:187], v[60:63]
	v_mfma_f32_16x16x32_bf16 v[56:59], v[152:155], v[184:187], v[56:59]
	v_mfma_f32_16x16x32_bf16 v[44:47], v[144:147], v[192:195], v[44:47]
	v_mfma_f32_16x16x32_bf16 v[40:43], v[152:155], v[192:195], v[40:43]
	v_mfma_f32_16x16x32_bf16 v[28:31], v[144:147], v[202:205], v[28:31]
	v_mfma_f32_16x16x32_bf16 v[24:27], v[152:155], v[202:205], v[24:27]
	v_mfma_f32_16x16x32_bf16 v[12:15], v[144:147], v[214:217], v[12:15]
	v_mfma_f32_16x16x32_bf16 v[8:11], v[152:155], v[214:217], v[8:11]
	v_mfma_f32_16x16x32_bf16 v[60:63], v[148:151], v[188:191], v[60:63]
	v_mfma_f32_16x16x32_bf16 v[56:59], v[156:159], v[188:191], v[56:59]
	v_mfma_f32_16x16x32_bf16 v[44:47], v[148:151], v[196:199], v[44:47]
	v_mfma_f32_16x16x32_bf16 v[40:43], v[156:159], v[196:199], v[40:43]
	v_mfma_f32_16x16x32_bf16 v[28:31], v[148:151], v[210:213], v[28:31]
	v_mfma_f32_16x16x32_bf16 v[24:27], v[156:159], v[210:213], v[24:27]
	v_mfma_f32_16x16x32_bf16 v[12:15], v[148:151], v[218:221], v[12:15]
	v_mfma_f32_16x16x32_bf16 v[8:11], v[156:159], v[218:221], v[8:11]
	v_mfma_f32_16x16x32_bf16 v[52:55], v[160:163], v[184:187], v[52:55]
	v_mfma_f32_16x16x32_bf16 v[48:51], v[176:179], v[184:187], v[48:51]
	v_mfma_f32_16x16x32_bf16 v[36:39], v[160:163], v[192:195], v[36:39]
	v_mfma_f32_16x16x32_bf16 v[32:35], v[176:179], v[192:195], v[32:35]
	v_mfma_f32_16x16x32_bf16 v[20:23], v[160:163], v[202:205], v[20:23]
	v_mfma_f32_16x16x32_bf16 v[16:19], v[176:179], v[202:205], v[16:19]
	v_mfma_f32_16x16x32_bf16 v[4:7], v[160:163], v[214:217], v[4:7]
	v_mfma_f32_16x16x32_bf16 v[0:3], v[176:179], v[214:217], v[0:3]
	v_mfma_f32_16x16x32_bf16 v[52:55], v[164:167], v[188:191], v[52:55]
	v_mfma_f32_16x16x32_bf16 v[48:51], v[180:183], v[188:191], v[48:51]
	v_mfma_f32_16x16x32_bf16 v[36:39], v[164:167], v[196:199], v[36:39]
	v_mfma_f32_16x16x32_bf16 v[32:35], v[180:183], v[196:199], v[32:35]
	v_mfma_f32_16x16x32_bf16 v[20:23], v[164:167], v[210:213], v[20:23]
	v_mfma_f32_16x16x32_bf16 v[16:19], v[180:183], v[210:213], v[16:19]
	v_mfma_f32_16x16x32_bf16 v[4:7], v[164:167], v[218:221], v[4:7]
	v_mfma_f32_16x16x32_bf16 v[0:3], v[180:183], v[218:221], v[0:3]
	s_barrier
	s_add_i32 s71, s71, 2
	s_add_u32 s38, s38, 0x100
	s_addc_u32 s39, s39, 0
	s_add_u32 s59, s59, 0x100
	s_addc_u32 s70, s70, 0
	s_cmp_gt_u32 s71, 13
	s_cbranch_scc0 .LBB0_977
	s_setprio 0
	s_and_b64 vcc, exec, s[18:19]
	s_cbranch_vccz .LBB0_980
	s_barrier
